# v12 plus one static s_setprio 1 for waves 4-7 around the A and B attention item loops (strategy: static priority raise for the younger half)
# baseline (speedup 1.0000x reference)
; DI int crow(int v, int h) { return (v & 3) + 8 * (v >> 2) + 4 * h; }
; DI int swz(int row) { return (((row >> 1) & 1) << 2) | ((row >> 2) & 3); }
; template <int MODE>
; DI void attn_seq(const Params& p, int layer, char* smem, const int tid, const int nitems, bf16_t* ob, const int ostride) {
;     ...
;   const int cs_blk = (MODE == 1) ? clampi(16 * (wv & 3) - 8, 0, 32) : 0;
;   auto make_lane = [&](const int cs) {
;     AttnLane L;
;     const int rr = r + cs, sw = swz(rr & 15);
;     L.kr0 = rr * 128 + ((0 + h) ^ sw) * 16; L.kr1 = rr * 128 + ((2 + h) ^ sw) * 16; L.kr2 = rr * 128 + ((4 + h) ^ sw) * 16; L.kr3 = rr * 128 + ((6 + h) ^ sw) * 16;
;     const int q = (lane & 15) >> 2, pp = lane & 3, g = (lane >> 4) & 1;
;     const int ra = cs + 4 * h + q, rb = ra + 8;
;     const int lp0 = 2 * g + (pp >> 1), lp1 = 4 + lp0;
;     L.vr00 = ra * 128 + ((lp0 ^ swz(ra & 15)) * 16) + 8 * (pp & 1); L.vr01 = rb * 128 + ((lp0 ^ swz(rb & 15)) * 16) + 8 * (pp & 1);
;     L.vr10 = ra * 128 + ((lp1 ^ swz(ra & 15)) * 16) + 8 * (pp & 1); L.vr11 = rb * 128 + ((lp1 ^ swz(rb & 15)) * 16) + 8 * (pp & 1);
;     return L;
;   };
;   const int drow = 8 * wv + (lane >> 3);
;   const int dlp = ((lane & 7) ^ swz(drow & 15)) * 8;
;     ...
; #pragma unroll
;     for (int v = 0; v < 16; ++v) {
;       st.o0[v] = 0.f; st.o1[v] = 0.f;
;       float ci = 0.f;
;       if (MODE == 1) {
;         const int cs_q = clampi(cq - 8, 0, 48);
;         const int kc = cs_blk + crow(v, h);
;         ci = (kc >= cs_q && kc < cs_q + 16) ? 0.f : -1e30f;
;       }
;       st.cinit[v] = ci;
;     }
;     st.m = 0.f; st.l = 0.f;
;     const int colbase = cs_blk - cq + 15 + 4 * h;
.LBB0_772:
	v_and_b32_e32 v5, 15, v2
	v_and_b32_e32 v4, 63, v2
	v_or_b32_e32 v154, s84, v5
	s_cmp_lg_u32 s84, 0
	v_lshrrev_b32_e32 v152, 5, v4
	v_subrev_co_u32_e32 v6, vcc, 8, v154
	s_cselect_b32 s96, s9, 0
	s_ashr_i32 s0, s2, 7
	v_min_u32_e32 v6, 48, v6
	v_lshlrev_b32_e32 v19, 2, v152
	s_and_b32 s97, s0, -2
	s_lshl_b32 s0, s6, 12
	v_cndmask_b32_e64 v17, v6, 0, vcc
	v_and_or_b32 v159, v3, 3, v19
	v_lshrrev_b32_e32 v3, 3, v2
	v_bfe_u32 v6, v2, 1, 1
	v_and_b32_e32 v151, 31, v2
	v_bfe_u32 v153, v2, 4, 1
	s_add_i32 s10, s0, 0
	v_and_or_b32 v160, v3, 2, v6
	v_lshlrev_b32_e32 v3, 1, v2
	v_bfe_u32 v2, v2, 2, 2
	s_add_i32 s10, s10, 0x18000
	v_lshlrev_b32_e32 v22, 3, v152
	v_and_or_b32 v25, v3, 4, v2
	v_lshlrev_b32_e32 v2, 7, v151
	v_add3_u32 v163, s10, v2, v22
	v_lshlrev_b32_e32 v2, 1, v140
	v_readlane_b32 s0, v255, 54
	v_or_b32_e32 v21, s96, v19
	v_add_u32_e32 v23, 16, v17
	v_and_b32_e32 v26, 4, v2
	v_lshlrev_b32_e32 v2, 4, v18
	v_mov_b32_e32 v3, v1
	v_readlane_b32 s1, v255, 55
	v_cmp_ge_u32_e32 vcc, v21, v17
	v_lshlrev_b32_e32 v5, 3, v4
	v_lshl_add_u64 v[132:133], s[0:1], 0, v[2:3]
	v_cmp_lt_u32_e64 s[0:1], v21, v23
	s_and_b64 s[0:1], vcc, s[0:1]
	v_or_b32_e32 v3, 1, v21
	v_cndmask_b32_e64 v2, v217, 0, s[0:1]
	v_cmp_ge_u32_e32 vcc, v3, v17
	v_cmp_lt_u32_e64 s[0:1], v3, v23
	v_lshlrev_b32_e32 v24, 4, v4
	s_and_b64 s[0:1], vcc, s[0:1]
	v_or_b32_e32 v4, 2, v21
	v_cndmask_b32_e64 v3, v217, 0, s[0:1]
	v_cmp_ge_u32_e32 vcc, v4, v17
	v_cmp_lt_u32_e64 s[0:1], v4, v23
	v_and_b32_e32 v20, 56, v5
	v_and_b32_e32 v162, 8, v5
	s_and_b64 s[0:1], vcc, s[0:1]
	v_or_b32_e32 v5, 3, v21
	v_cndmask_b32_e64 v4, v217, 0, s[0:1]
	v_cmp_ge_u32_e32 vcc, v5, v17
	v_cmp_lt_u32_e64 s[0:1], v5, v23
	s_and_b64 s[0:1], vcc, s[0:1]
	v_add_u32_e32 v6, 8, v21
	v_cndmask_b32_e64 v5, v217, 0, s[0:1]
	v_cmp_ge_u32_e32 vcc, v6, v17
	v_cmp_lt_u32_e64 s[0:1], v6, v23
	s_and_b64 s[0:1], vcc, s[0:1]
	v_add_u32_e32 v7, 9, v21
	v_cndmask_b32_e64 v6, v217, 0, s[0:1]
	v_cmp_ge_u32_e32 vcc, v7, v17
	v_cmp_lt_u32_e64 s[0:1], v7, v23
	s_and_b64 s[0:1], vcc, s[0:1]
	v_add_u32_e32 v8, 10, v21
	v_cndmask_b32_e64 v7, v217, 0, s[0:1]
	v_cmp_ge_u32_e32 vcc, v8, v17
	v_cmp_lt_u32_e64 s[0:1], v8, v23
	s_and_b64 s[0:1], vcc, s[0:1]
	v_add_u32_e32 v9, 11, v21
	v_cndmask_b32_e64 v8, v217, 0, s[0:1]
	v_cmp_ge_u32_e32 vcc, v9, v17
	v_cmp_lt_u32_e64 s[0:1], v9, v23
	s_and_b64 s[0:1], vcc, s[0:1]
	v_add_u32_e32 v10, 16, v21
	v_cndmask_b32_e64 v9, v217, 0, s[0:1]
	v_cmp_ge_u32_e32 vcc, v10, v17
	v_cmp_lt_u32_e64 s[0:1], v21, v17
	s_and_b64 s[0:1], vcc, s[0:1]
	v_add_u32_e32 v11, 17, v21
	v_cndmask_b32_e64 v10, v217, 0, s[0:1]
	v_cmp_ge_u32_e32 vcc, v11, v17
	v_cmp_lt_u32_e64 s[0:1], v11, v23
	s_and_b64 s[0:1], vcc, s[0:1]
	v_add_u32_e32 v12, 18, v21
	v_cndmask_b32_e64 v11, v217, 0, s[0:1]
	v_cmp_ge_u32_e32 vcc, v12, v17
	v_cmp_lt_u32_e64 s[0:1], v12, v23
	s_and_b64 s[0:1], vcc, s[0:1]
	v_add_u32_e32 v13, 19, v21
	v_cndmask_b32_e64 v12, v217, 0, s[0:1]
	v_cmp_ge_u32_e32 vcc, v13, v17
	v_cmp_lt_u32_e64 s[0:1], v13, v23
	s_and_b64 s[0:1], vcc, s[0:1]
	v_add_u32_e32 v14, 24, v21
	v_cndmask_b32_e64 v13, v217, 0, s[0:1]
	v_cmp_ge_u32_e32 vcc, v14, v17
	v_cmp_lt_u32_e64 s[0:1], v14, v23
	s_and_b64 s[0:1], vcc, s[0:1]
	v_add_u32_e32 v15, 25, v21
	v_cndmask_b32_e64 v14, v217, 0, s[0:1]
	v_cmp_ge_u32_e32 vcc, v15, v17
	v_cmp_lt_u32_e64 s[0:1], v15, v23
	s_and_b64 s[0:1], vcc, s[0:1]
	v_add_u32_e32 v16, 26, v21
	v_cndmask_b32_e64 v15, v217, 0, s[0:1]
	v_cmp_ge_u32_e32 vcc, v16, v17
	v_cmp_lt_u32_e64 s[0:1], v16, v23
	v_or_b32_e32 v166, 8, v140
	v_or_b32_e32 v35, 24, v140
	s_and_b64 s[0:1], vcc, s[0:1]
	v_add_u32_e32 v21, 27, v21
	v_lshrrev_b32_e32 v34, 2, v166
	v_lshl_add_u32 v36, v35, 7, s10
	v_bfe_u32 v35, v35, 2, 2
	v_cndmask_b32_e64 v16, v217, 0, s[0:1]
	v_cmp_ge_u32_e32 vcc, v21, v17
	v_cmp_lt_u32_e64 s[0:1], v21, v23
	v_lshlrev_b32_e32 v165, 4, v25
	v_bitop3_b32 v32, v26, v18, v152 bitop3:0x36
	v_bitop3_b32 v34, v34, v18, v26 bitop3:0x36
	v_bitop3_b32 v18, v35, v18, v26 bitop3:0x36
	v_sub_u32_e32 v19, v19, v154
	s_add_i32 s7, s7, -4
	v_or_b32_e32 v155, s84, v140
	s_and_b64 s[0:1], vcc, s[0:1]
	v_xor_b32_e32 v21, 64, v165
	v_xor_b32_e32 v23, 16, v165
	v_xor_b32_e32 v25, 0x50, v165
	v_xor_b32_e32 v27, 32, v165
	v_xor_b32_e32 v28, 0x60, v165
	v_xor_b32_e32 v29, 48, v165
	v_xor_b32_e32 v30, 0x70, v165
	v_lshl_add_u32 v31, v140, 7, s10
	v_lshlrev_b32_e32 v32, 4, v32
	v_lshl_add_u32 v33, v166, 7, s10
	v_lshlrev_b32_e32 v34, 4, v34
	v_lshlrev_b32_e32 v18, 4, v18
	v_add_u32_e32 v19, s96, v19
	s_mov_b32 s87, 0
	s_add_i32 s26, s15, -1
	v_or_b32_e32 v156, 2, v152
	v_or_b32_e32 v157, 4, v152
	v_or_b32_e32 v158, 6, v152
	v_or_b32_e32 v161, 4, v160
	v_or_b32_e32 v164, 8, v155
	v_cndmask_b32_e64 v17, v217, 0, s[0:1]
	v_bitop3_b32 v167, v140, 15, 24 bitop3:0xc8
	v_mov_b32_e32 v173, s7
	v_lshlrev_b32_e32 v134, 1, v20
	v_lshlrev_b32_e32 v136, 1, v22
	v_lshlrev_b32_e32 v168, 2, v19
	v_add_u32_e32 v169, s10, v24
	v_add_u32_e32 v170, v163, v21
	v_add_u32_e32 v171, v163, v23
	v_add_u32_e32 v172, v163, v25
	v_add_u32_e32 v174, v163, v27
	v_add_u32_e32 v175, v163, v28
	v_add_u32_e32 v176, v163, v29
	v_add_u32_e32 v177, v163, v30
	v_add_u32_e32 v178, v31, v32
	v_add_u32_e32 v179, v33, v34
	v_add_u32_e32 v180, v36, v18
	s_mov_b32 s33, 0
	v_readfirstlane_b32 s100, v208
	s_nop 3
	s_lshr_b32 s100, s100, 8
	s_cmp_eq_u32 s100, 0
	s_cbranch_scc1 .Lm1_noprio
	s_setprio 1
.Lm1_noprio:
	s_branch .LBB0_775
.LBB0_773:
	v_mov_b32_e32 v98, 0
	v_mov_b32_e32 v99, v98
	v_mov_b32_e32 v100, v98
	v_mov_b32_e32 v101, v98
	v_mov_b32_e32 v102, v98
	v_mov_b32_e32 v103, v98
	v_mov_b32_e32 v104, v98
	v_mov_b32_e32 v105, v98
	v_mov_b32_e32 v106, v98
	v_mov_b32_e32 v107, v98
	v_mov_b32_e32 v108, v98
	v_mov_b32_e32 v109, v98
	v_mov_b32_e32 v110, v98
	v_mov_b32_e32 v111, v98
	v_mov_b32_e32 v112, v98
	v_mov_b32_e32 v113, v98
	v_mov_b64_e32 v[66:67], v[98:99]
	v_mov_b64_e32 v[82:83], v[98:99]
	v_mov_b64_e32 v[68:69], v[100:101]
	v_mov_b64_e32 v[70:71], v[102:103]
	v_mov_b64_e32 v[72:73], v[104:105]
	v_mov_b64_e32 v[74:75], v[106:107]
	v_mov_b64_e32 v[76:77], v[108:109]
	v_mov_b64_e32 v[78:79], v[110:111]
	v_mov_b64_e32 v[80:81], v[112:113]
	v_mov_b64_e32 v[84:85], v[100:101]
	v_mov_b64_e32 v[86:87], v[102:103]
	v_mov_b64_e32 v[88:89], v[104:105]
	v_mov_b64_e32 v[90:91], v[106:107]
	v_mov_b64_e32 v[92:93], v[108:109]
	v_mov_b64_e32 v[94:95], v[110:111]
	v_mov_b64_e32 v[96:97], v[112:113]

; DI int opaque_tid() { int t = threadIdx.x; asm volatile("" : "+v"(t)); return t; }
; DI void attn_phase(const Params& p, int layer, char* smem, bf16_t* ob, const int ostride) {
;     ...
;     { const int tid = opaque_tid(); attn_seq<1>(p, layer, smem, tid, 4096, ob, ostride); }
;     if (ctx_out) { const int tid = opaque_tid(); attn_seq<3>(p, layer, smem, tid, 512, ob, ostride); }
.LBB0_809:
	s_setprio 0
	v_readlane_b32 s86, v255, 44
	v_readlane_b32 s87, v255, 45
	s_movk_i32 s91, 0x1000
	s_movk_i32 s90, 0x2000
	s_mov_b32 s96, 0x800000
	s_movk_i32 s97, 0x104
	s_mov_b64 s[76:77], s[4:5]

; #define LAS3 __attribute__((address_space(3)))
; DI int swz(int row) { return (((row >> 1) & 1) << 2) | ((row >> 2) & 3); }
; template <int MODE>
; DI void attn_seq(const Params& p, int layer, char* smem, const int tid, const int nitems, bf16_t* ob, const int ostride) {
;     ...
;   auto make_lane = [&](const int cs) {
;     AttnLane L;
;     const int rr = r + cs, sw = swz(rr & 15);
;     L.kr0 = rr * 128 + ((0 + h) ^ sw) * 16; L.kr1 = rr * 128 + ((2 + h) ^ sw) * 16; L.kr2 = rr * 128 + ((4 + h) ^ sw) * 16; L.kr3 = rr * 128 + ((6 + h) ^ sw) * 16;
;     const int q = (lane & 15) >> 2, pp = lane & 3, g = (lane >> 4) & 1;
;     const int ra = cs + 4 * h + q, rb = ra + 8;
;     const int lp0 = 2 * g + (pp >> 1), lp1 = 4 + lp0;
;     L.vr00 = ra * 128 + ((lp0 ^ swz(ra & 15)) * 16) + 8 * (pp & 1); L.vr01 = rb * 128 + ((lp0 ^ swz(rb & 15)) * 16) + 8 * (pp & 1);
;     L.vr10 = ra * 128 + ((lp1 ^ swz(ra & 15)) * 16) + 8 * (pp & 1); L.vr11 = rb * 128 + ((lp1 ^ swz(rb & 15)) * 16) + 8 * (pp & 1);
;     return L;
;   };
;   const int drow = 8 * wv + (lane >> 3);
;   const int dlp = ((lane & 7) ^ swz(drow & 15)) * 8;
;   auto issue = [&](const ItemD& d, int u, int stage) {
; #pragma unroll
;     for (int c = 0; c < 2; ++c) {
;       int tok;
;       if (u < 2) tok = TL + d.b * 256 + (2 * u + c) * 64 + drow;
;       else if (MODE == 0) tok = d.b * 2048 + clampi(d.a0 + 64 * (2 * (u - 2) + c) + drow, 0, 2047);
;       else tok = d.b * 2048 + min(d.a0 + 2 * (u - 2) + c, d.a1) * 64 + drow;
;       const bf16_t* g = p.qkvg + (size_t)tok * NW + d.hk * 64 + dlp;
;       __builtin_amdgcn_global_load_lds((const unsigned*)(g + koff), (LAS3 unsigned*)(lds + stage * ATT_STAGE + c * 8192 + wv * 1024), 16, 0, 0);
;       __builtin_amdgcn_global_load_lds((const unsigned*)(g + voff), (LAS3 unsigned*)(lds + stage * ATT_STAGE + 16384 + c * 8192 + wv * 1024), 16, 0, 0);
;     }
;   };
;   int gk = 0, gu = 0;
;   ItemD gd = item_desc<MODE>(item0);
;   int sa = 0;
;   bool gvalid = true;
;   auto gen_issue = [&]() {
;     issue(gd, gu, sa);
;     sa = (sa == ATT_NST - 1) ? 0 : sa + 1;
;     if (++gu == gd.nt) { gu = 0; ++gk; if (gk < nit) gd = item_desc<MODE>(item0 + gk); else gvalid = false; }
;   };
;   __syncthreads();
;   gen_issue();
;   if (gvalid) gen_issue();
.LBB0_843:
	s_sub_i32 s7, s0, s6
	s_cmp_lt_i32 s7, 1
	s_cbranch_scc1 .LBB0_876
	s_ashr_i32 s8, s10, 6
	s_lshl_b32 s85, s8, 3
	v_bfe_u32 v134, v2, 3, 3
	v_or_b32_e32 v11, s85, v134
	s_ashr_i32 s35, s6, 7
	v_lshrrev_b32_e32 v4, 2, v2
	s_lshl_b32 s9, s35, 8
	v_add_u32_e32 v135, 0x10000, v11
	v_and_b32_e32 v12, 7, v2
	v_bfe_u32 v0, v11, 2, 2
	v_and_b32_e32 v13, 4, v4
	s_bfe_u32 s70, s6, 0x20005
	v_add_u32_e32 v6, s9, v135
	v_mov_b64_e32 v[4:5], s[38:39]
	v_bitop3_b32 v0, v13, v12, v0 bitop3:0x36
	v_mad_i64_i32 v[6:7], s[0:1], v6, s92, v[4:5]
	s_lshl_b32 s78, s70, 7
	v_lshlrev_b32_e32 v112, 3, v0
	v_lshl_add_u64 v[6:7], v[6:7], 0, s[78:79]
	v_lshlrev_b32_e32 v0, 4, v0
	s_lshl_b32 s0, s8, 10
	v_lshl_add_u64 v[6:7], v[6:7], 0, v[0:1]
	s_add_i32 s71, s0, 0
	v_lshl_add_u64 v[8:9], v[6:7], 0, s[80:81]
	s_mov_b32 m0, s71
	s_mov_b64 s[10:11], 0xa00
	s_waitcnt vmcnt(0)
	s_barrier
	global_load_lds_dwordx4 v[8:9], off
	v_lshl_add_u64 v[6:7], v[6:7], 0, s[10:11]
	s_add_i32 m0, s71, 0x4000
	v_add_u32_e32 v136, 0x10040, v11
	global_load_lds_dwordx4 v[6:7], off
	v_add_u32_e32 v6, s9, v136
	v_mad_i64_i32 v[6:7], s[0:1], v6, s92, v[4:5]
	v_lshl_add_u64 v[6:7], v[6:7], 0, s[78:79]
	v_lshl_add_u64 v[6:7], v[6:7], 0, v[0:1]
	v_lshl_add_u64 v[8:9], v[6:7], 0, s[80:81]
	s_add_i32 m0, s71, 0x2000
	v_lshl_add_u64 v[6:7], v[6:7], 0, s[10:11]
	global_load_lds_dwordx4 v[8:9], off
	s_add_i32 m0, s71, 0x6000
	s_lshl_b32 s0, s6, 6
	v_add_u32_e32 v14, s9, v11
	global_load_lds_dwordx4 v[6:7], off
	s_and_b32 s0, s0, 0x7c0
	v_add_u32_e32 v6, 0x10080, v14
	s_add_i32 s75, s0, 0xffffff80
	v_mad_i64_i32 v[6:7], s[0:1], v6, s92, v[4:5]
	v_lshl_add_u64 v[6:7], v[6:7], 0, s[78:79]
	v_lshl_add_u64 v[6:7], v[6:7], 0, v[0:1]
	v_lshl_add_u64 v[8:9], v[6:7], 0, s[80:81]
	s_add_i32 m0, s71, 0x8000
	v_lshl_add_u64 v[6:7], v[6:7], 0, s[10:11]
	global_load_lds_dwordx4 v[8:9], off
	s_add_i32 m0, s71, 0xc000
	v_and_b32_e32 v133, 31, v2
	global_load_lds_dwordx4 v[6:7], off
	v_add_u32_e32 v6, 0x100c0, v14
	v_mad_i64_i32 v[4:5], s[0:1], v6, s92, v[4:5]
	v_lshl_add_u64 v[4:5], v[4:5], 0, s[78:79]
	v_lshl_add_u64 v[4:5], v[4:5], 0, v[0:1]
	v_lshl_add_u64 v[6:7], v[4:5], 0, s[80:81]
	s_add_i32 m0, s71, 0xa000
	v_lshl_add_u64 v[4:5], v[4:5], 0, s[10:11]
	global_load_lds_dwordx4 v[6:7], off
	s_add_i32 m0, s71, 0xe000
	v_bfe_u32 v10, v2, 5, 1
	global_load_lds_dwordx4 v[4:5], off
	v_lshlrev_b32_e32 v5, 1, v2
	v_and_b32_e32 v5, 4, v5
	v_bfe_u32 v7, v2, 2, 2
	v_add_u32_e32 v137, 0xffffff00, v11
	v_add_u32_e32 v138, 0xffffff40, v11
	v_lshlrev_b32_e32 v9, 7, v133
	v_bitop3_b32 v11, v5, v10, v7 bitop3:0x36
	v_lshl_or_b32 v139, v11, 4, v9
	v_or_b32_e32 v11, 2, v10
	v_bitop3_b32 v11, v5, v11, v7 bitop3:0x36
	v_lshl_or_b32 v140, v11, 4, v9
	v_or_b32_e32 v11, 4, v10
	v_bitop3_b32 v11, v5, v11, v7 bitop3:0x36
	v_lshl_or_b32 v141, v11, 4, v9
	v_or_b32_e32 v11, 6, v10
	v_and_b32_e32 v3, 63, v2
	v_or_b32_e32 v8, v5, v7
	v_bitop3_b32 v5, v5, v11, v7 bitop3:0x36
	v_lshrrev_b32_e32 v11, 3, v2
	v_lshrrev_b32_e32 v14, 1, v2
	v_bfe_u32 v2, v2, 1, 1
	v_lshlrev_b32_e32 v148, 2, v10
	v_and_or_b32 v2, v11, 2, v2
	v_and_b32_e32 v14, 4, v14
	v_lshlrev_b32_e32 v0, 3, v3
	v_lshl_or_b32 v142, v5, 4, v9
	v_or_b32_e32 v5, v148, v7
	v_bitop3_b32 v15, v14, v2, v10 bitop3:0x36
	v_and_b32_e32 v4, 56, v0
	v_or_b32_e32 v7, 8, v5
	v_lshlrev_b32_e32 v5, 7, v5
	v_lshlrev_b32_e32 v15, 4, v15
	v_and_b32_e32 v0, 8, v0
	v_or3_b32 v149, v15, v5, v0
	v_lshlrev_b32_e32 v15, 7, v7
	v_lshrrev_b32_e32 v7, 2, v7
	v_or_b32_e32 v11, 4, v2
	v_bitop3_b32 v2, v7, v2, v14 bitop3:0x36
	v_lshl_add_u32 v2, v2, 4, v15
	v_or_b32_e32 v150, v2, v0
	v_bitop3_b32 v2, v14, v11, v10 bitop3:0x36
	s_lshl_b32 s0, s8, 12
	v_lshlrev_b32_e32 v2, 4, v2
	s_add_i32 s86, s0, 0
	v_or3_b32 v151, v2, v5, v0
	v_bitop3_b32 v2, v7, v11, v14 bitop3:0x36
	v_readlane_b32 s0, v255, 46
	v_or_b32_e32 v155, 8, v134
	v_or_b32_e32 v157, 24, v134
	v_lshl_add_u32 v2, v2, 4, v15
	s_lshl_b32 s88, s0, 3
	v_readlane_b32 s0, v255, 54
	v_lshrrev_b32_e32 v16, 2, v155
	v_bfe_u32 v19, v157, 2, 2
	s_add_i32 s86, s86, 0x18000
	v_lshlrev_b32_e32 v6, 3, v10
	v_or_b32_e32 v152, v2, v0
	v_lshlrev_b32_e32 v0, 4, v12
	v_readlane_b32 s1, v255, 55
	v_lshlrev_b32_e32 v154, 4, v8
	v_bitop3_b32 v10, v13, v12, v10 bitop3:0x36
	v_bitop3_b32 v16, v16, v12, v13 bitop3:0x36
	v_or_b32_e32 v156, 16, v134
	v_bitop3_b32 v12, v19, v12, v13 bitop3:0x36
	v_lshlrev_b32_e32 v2, 4, v3
	v_add3_u32 v153, s86, v9, v6
	v_lshl_add_u64 v[114:115], s[0:1], 0, v[0:1]
	v_xor_b32_e32 v0, 64, v154
	v_xor_b32_e32 v3, 16, v154
	v_xor_b32_e32 v5, 0x50, v154
	v_xor_b32_e32 v7, 32, v154
	v_xor_b32_e32 v8, 0x60, v154
	v_xor_b32_e32 v9, 48, v154
	v_xor_b32_e32 v11, 0x70, v154
	v_lshl_add_u32 v14, v134, 7, s86
	v_lshlrev_b32_e32 v10, 4, v10
	v_lshl_add_u32 v15, v155, 7, s86
	v_lshlrev_b32_e32 v16, 4, v16
	v_lshl_add_u32 v17, v156, 7, s86
	v_lshl_add_u32 v18, v157, 7, s86
	v_lshlrev_b32_e32 v12, 4, v12
	s_mov_b32 s34, 2
	s_mov_b64 s[4:5], 0xa00
	s_and_b32 s84, s8, 3
	s_andn2_b32 s85, s85, 31
	s_add_i32 s87, s7, -1
	s_mov_b64 s[8:9], -1
	s_mov_b32 s89, 0
	v_lshlrev_b32_e32 v116, 1, v4
	v_lshlrev_b32_e32 v118, 1, v6
	v_add_u32_e32 v158, s86, v2
	v_add_u32_e32 v159, v153, v0
	v_add_u32_e32 v160, v153, v3
	v_add_u32_e32 v161, v153, v5
	v_add_u32_e32 v162, v153, v7
	v_add_u32_e32 v163, v153, v8
	v_add_u32_e32 v164, v153, v9
	v_add_u32_e32 v165, v153, v11
	v_add_u32_e32 v166, v14, v10
	v_add_u32_e32 v167, v15, v16
	v_add_u32_e32 v168, v17, v10
	v_add_u32_e32 v169, v18, v12
	s_mov_b32 s96, 0
	s_mov_b32 s97, 0
	s_mov_b32 s12, 2
	s_cmp_eq_u32 s85, 0
	s_cbranch_scc1 .Lm0_noprio
	s_setprio 1
.Lm0_noprio:
	s_branch .LBB0_846
.LBB0_845:
	s_add_i32 s100, s96, 1
	s_cmp_ge_i32 s100, s7
	s_cbranch_scc1 .Lm0_noprefetch
	s_add_i32 s100, s100, s6
	s_lshl_b32 s101, s100, 6
	s_and_b32 s101, s101, 0x7c0
	s_add_i32 s101, s101, s85
	s_lshl_b32 vcc_lo, s100, 4
	s_and_b32 vcc_lo, vcc_lo, 0xfffff800
	s_add_i32 s101, s101, vcc_lo
	s_lshr_b32 s100, s100, 3
	s_and_b32 s100, s100, 12
	s_or_b32 s100, s100, s84
	s_lshl_b32 s100, s100, 7
	v_or_b32_e32 v100, s101, v133
	v_mov_b64_e32 v[98:99], s[38:39]
	s_mov_b32 s101, 0
	v_mad_i64_i32 v[96:97], vcc, v100, s92, v[98:99]
	v_mov_b32_e32 v102, v118
	v_mov_b32_e32 v103, 0
	v_lshl_add_u64 v[96:97], v[96:97], 0, s[100:101]
	v_lshl_add_u64 v[96:97], v[96:97], 0, v[102:103]
	global_load_dwordx4 v[108:111], v[96:97], off offset:96
	global_load_dwordx4 v[104:107], v[96:97], off offset:64
	global_load_dwordx4 v[100:103], v[96:97], off offset:32
	global_load_dwordx4 v[96:99], v[96:97], off

; DI int opaque_tid() { int t = threadIdx.x; asm volatile("" : "+v"(t)); return t; }
; DI void attn_phase(const Params& p, int layer, char* smem, bf16_t* ob, const int ostride) {
;     ...
;     { const int tid = opaque_tid(); attn_seq<0>(p, layer, smem, tid, 4096, ob, ostride); }
;     if (ctx_out) { const int tid = opaque_tid(); attn_seq<2>(p, layer, smem, tid, 512, ob, ostride); }
.LBB0_875:
	s_setprio 0
	v_readlane_b32 s86, v255, 44
	v_readlane_b32 s87, v255, 45
	s_movk_i32 s90, 0x2000
	s_mov_b32 s96, 0x800000
	s_movk_i32 s97, 0x104
	s_mov_b64 s[88:89], 0x1000
